# grid barrier: the workgroup that arrives 12 before the last on its XCD issues one un-waited L2 writeback (head start for the leader's writeback); on top of all-to-all release
# baseline (speedup 1.0000x reference)
.Lxb_nl_0:
	s_and_saveexec_b64 s[4:5], vcc
	s_xor_b64 s[4:5], exec, s[4:5]
	s_cbranch_execz .LBB0_260
	v_sub_u32_e32 v7, v4, v6
	v_cmp_eq_u32_e32 vcc, 12, v7
	s_cbranch_vccz .Lxb_nf_0
	buffer_wbl2 sc1
.Lxb_nf_0:
	v_mov_b32_e32 v2, s38
	v_add_co_u32_e32 v4, vcc, 0x2000, v2
	v_mov_b32_e32 v2, s28
	s_nop 0
	v_addc_co_u32_e32 v5, vcc, 0, v2, vcc
	flat_load_dword v2, v[4:5] offset:1024 sc1
	s_add_u32 s10, s38, 0x2400
	s_addc_u32 s11, s28, 0
	s_waitcnt vmcnt(0) lgkmcnt(0)
	v_cmp_lt_u32_e32 vcc, v2, v3
	s_and_saveexec_b64 s[8:9], vcc
	s_cbranch_execz .LBB0_259
	s_mov_b32 s39, 1
	s_mov_b64 s[12:13], 0
	s_branch .LBB0_251

.Lxb_nf_3:
	v_mov_b32_e32 v2, s36
	v_add_co_u32_e32 v4, vcc, 0x2000, v2
	v_mov_b32_e32 v2, s28
	s_nop 0
	v_addc_co_u32_e32 v5, vcc, 0, v2, vcc
	flat_load_dword v2, v[4:5] offset:1024 sc1
	s_add_u32 s8, s36, 0x2400
	s_addc_u32 s9, s28, 0
	s_waitcnt vmcnt(0) lgkmcnt(0)
	v_cmp_lt_u32_e32 vcc, v2, v3
	s_and_saveexec_b64 s[6:7], vcc
	s_cbranch_execz .LBB0_1376
	s_mov_b32 s37, 1
	s_mov_b64 s[10:11], 0
	s_branch .LBB0_1368

.Lxb_nf_5:
	v_mov_b32_e32 v2, s38
	v_add_co_u32_e32 v4, vcc, 0x2000, v2
	v_mov_b32_e32 v2, s28
	s_nop 0
	v_addc_co_u32_e32 v5, vcc, 0, v2, vcc
	flat_load_dword v2, v[4:5] offset:1024 sc1
	s_add_u32 s8, s38, 0x2400
	s_addc_u32 s9, s28, 0
	s_waitcnt vmcnt(0) lgkmcnt(0)
	v_cmp_lt_u32_e32 vcc, v2, v3
	s_and_saveexec_b64 s[6:7], vcc
	s_cbranch_execz .LBB0_1535
	s_mov_b32 s39, 1
	s_mov_b64 s[10:11], 0
	s_branch .LBB0_1527

.Lxb_nf_8:
	v_mov_b32_e32 v2, s28
	v_add_co_u32_e32 v4, vcc, 0x2000, v2
	v_mov_b32_e32 v2, s25
	s_nop 0
	v_addc_co_u32_e32 v5, vcc, 0, v2, vcc
	flat_load_dword v2, v[4:5] offset:1024 sc1
	s_add_u32 s8, s28, 0x2400
	s_addc_u32 s9, s25, 0
	s_waitcnt vmcnt(0) lgkmcnt(0)
	v_cmp_lt_u32_e32 vcc, v2, v3
	s_and_saveexec_b64 s[6:7], vcc
	s_cbranch_execz .LBB0_1807
	s_mov_b32 s36, 1
	s_mov_b64 s[10:11], 0
	s_branch .LBB0_1799
